# streaming cache policy: nt on P1's x-row loads (not re-read before P8) on top of the P13 nt stores
# speedup vs baseline: 1.0001x; 1.0001x over previous
; #define GAS __attribute__((address_space(1)))
; __device__ __forceinline__ void norm_phase(const Args& a, LAS unsigned char* lds, int layer, const float* xlat, const float* xctx, int nrows, const bf16* yadd, bf16* xout) {
;     ...
;     const int gw = blockIdx.x * NWAVES + wave, NGW = gridDim.x * NWAVES;
;     f32x4 v[16], vn[16]; v2u yv[16], yn[16];
;     auto loadrow = [&](int row, f32x4 (&dst)[16], v2u (&yd)[16]) {
;         const float* xr = (row < MLAT) ? xlat + (size_t)row * D : xctx + (size_t)(row - MLAT) * D;
;         const GAS f32x4* xp = (const GAS f32x4*)xr + lane;
; #pragma unroll
;         for (int q = 0; q < 16; ++q) dst[q] = xp[64 * q];
;         if (yadd) { const GAS v2u* yp = (const GAS v2u*)(yadd + (size_t)row * D) + lane;
; #pragma unroll
;             for (int q = 0; q < 16; ++q) yd[q] = yp[64 * q]; }
;     };
;     int row = gw;
;     if (row < nrows) loadrow(row, v, yv);
.LBB0_289:
	s_or_b64 exec, exec, s[0:1]
	s_ashr_i32 s0, s16, 6
	s_add_i32 s12, s0, s33
	s_cmpk_lt_i32 s12, 0x4200
	s_waitcnt lgkmcnt(0)
	s_barrier
	s_cbranch_scc0 .LBB0_294
	s_add_i32 s0, s12, 0xffffc000
	s_ashr_i32 s13, s12, 31
	s_cmpk_lt_i32 s12, 0x4000
	s_cselect_b32 s1, s13, 0
	s_cselect_b32 s0, s12, s0
	s_cselect_b32 s6, s53, s57
	s_cselect_b32 s7, s52, s56
	s_lshl_b64 s[0:1], s[0:1], 14
	s_waitcnt vmcnt(11)
	v_and_b32_e32 v22, 63, v2
	s_add_u32 s0, s7, s0
	s_addc_u32 s1, s6, s1
	v_mov_b32_e32 v131, 0
	v_lshlrev_b32_e32 v130, 4, v22
	v_lshl_add_u64 v[2:3], s[0:1], 0, v[130:131]
	s_movk_i32 s10, 0x1000
	v_add_co_u32_e32 v4, vcc, s10, v2
	s_movk_i32 s6, 0x2000
	s_nop 0
	v_addc_co_u32_e32 v5, vcc, 0, v3, vcc
	v_add_co_u32_e32 v6, vcc, s6, v2
	s_movk_i32 s6, 0x3000
	s_nop 0
	v_addc_co_u32_e32 v7, vcc, 0, v3, vcc
	global_load_dwordx4 v[122:125], v130, s[0:1] offset:1024 nt
	global_load_dwordx4 v[118:121], v130, s[0:1] offset:2048 nt
	global_load_dwordx4 v[114:117], v130, s[0:1] offset:3072 nt
	global_load_dwordx4 v[110:113], v[6:7], off offset:-4096 nt
	global_load_dwordx4 v[106:109], v[4:5], off offset:1024 nt
	global_load_dwordx4 v[102:105], v[4:5], off offset:2048 nt
	global_load_dwordx4 v[94:97], v[6:7], off nt
	global_load_dwordx4 v[90:93], v[6:7], off offset:1024 nt
	global_load_dwordx4 v[86:89], v[6:7], off offset:2048 nt
	global_load_dwordx4 v[18:21], v[6:7], off offset:3072 nt
	v_add_co_u32_e32 v2, vcc, s6, v2
	v_mbcnt_lo_u32_b32 v1, -1, 0
	s_nop 0
	v_addc_co_u32_e32 v3, vcc, 0, v3, vcc
	global_load_dwordx4 v[98:101], v[4:5], off offset:3072 nt
	global_load_dwordx4 v[14:17], v[2:3], off nt
	global_load_dwordx4 v[10:13], v[2:3], off offset:1024 nt
	global_load_dwordx4 v[6:9], v[2:3], off offset:2048 nt
	global_load_dwordx4 v[126:129], v130, s[0:1] nt
	s_nop 0
	global_load_dwordx4 v[2:5], v[2:3], off offset:3072 nt
	s_waitcnt vmcnt(26)
	v_mbcnt_hi_u32_b32 v23, -1, v1
	v_and_b32_e32 v1, 64, v23
	s_waitcnt vmcnt(25)
	v_add_u32_e32 v24, 64, v1
	v_xor_b32_e32 v1, 1, v23
	v_cmp_lt_i32_e32 vcc, v1, v24
	s_waitcnt vmcnt(24)
	v_xor_b32_e32 v25, 2, v23
	s_lshl_b64 s[0:1], s[12:13], 13
	v_cndmask_b32_e32 v1, v23, v1, vcc
	v_cmp_lt_i32_e32 vcc, v25, v24
	s_add_u32 s0, s24, s0
	v_add_u32_e32 v140, 0, v130
	v_cndmask_b32_e32 v25, v23, v25, vcc
	v_lshlrev_b32_e32 v135, 2, v25
	v_xor_b32_e32 v25, 4, v23
	v_cmp_lt_i32_e32 vcc, v25, v24
	v_lshlrev_b32_e32 v130, 3, v22
	s_addc_u32 s1, s25, s1
	v_cndmask_b32_e32 v25, v23, v25, vcc
	v_lshlrev_b32_e32 v136, 2, v25
	v_xor_b32_e32 v25, 8, v23
	v_cmp_lt_i32_e32 vcc, v25, v24
	s_ashr_i32 s49, s48, 31
	v_lshlrev_b32_e32 v1, 2, v1
	v_cndmask_b32_e32 v25, v23, v25, vcc
	v_lshlrev_b32_e32 v137, 2, v25
	v_xor_b32_e32 v25, 16, v23
	v_cmp_lt_i32_e32 vcc, v25, v24
	s_lshl_b64 s[6:7], s[48:49], 13
	v_mov_b32_e32 v141, 0x358637bd
	v_cndmask_b32_e32 v25, v23, v25, vcc
	v_lshlrev_b32_e32 v138, 2, v25
	v_xor_b32_e32 v25, 32, v23
	v_cmp_lt_i32_e32 vcc, v25, v24
	s_mov_b32 s11, 0xf800000
	v_mov_b32_e32 v142, 0x260
	v_cndmask_b32_e32 v23, v23, v25, vcc
	v_lshl_add_u64 v[24:25], s[0:1], 0, v[130:131]
	s_mov_b64 s[0:1], 0x1a900000
	v_lshlrev_b32_e32 v139, 2, v23
	v_lshl_add_u64 v[132:133], v[24:25], 0, s[0:1]
	v_lshlrev_b32_e32 v130, 4, v22
	s_branch .LBB0_292

; #define GAS __attribute__((address_space(1)))
; __device__ __forceinline__ void norm_phase(const Args& a, LAS unsigned char* lds, int layer, const float* xlat, const float* xctx, int nrows, const bf16* yadd, bf16* xout) {
;     ...
;     auto loadrow = [&](int row, f32x4 (&dst)[16], v2u (&yd)[16]) {
;         const float* xr = (row < MLAT) ? xlat + (size_t)row * D : xctx + (size_t)(row - MLAT) * D;
;         const GAS f32x4* xp = (const GAS f32x4*)xr + lane;
; #pragma unroll
;         for (int q = 0; q < 16; ++q) dst[q] = xp[64 * q];
;         if (yadd) { const GAS v2u* yp = (const GAS v2u*)(yadd + (size_t)row * D) + lane;
; #pragma unroll
;             for (int q = 0; q < 16; ++q) yd[q] = yp[64 * q]; }
;     };
;     int row = gw;
;     if (row < nrows) loadrow(row, v, yv);
;     while (row < nrows) {
;         const int nrow = row + NGW;
;         if (nrow < nrows) loadrow(nrow, vn, yn);
.LBB0_292:
	s_add_i32 s13, s12, s48
	s_cmpk_gt_i32 s13, 0x41ff
	s_cselect_b64 s[8:9], -1, 0
	s_and_b64 vcc, exec, s[8:9]
	s_cbranch_vccnz .LBB0_291
	s_add_i32 s0, s13, 0xffffc000
	s_ashr_i32 s1, s13, 31
	s_cmpk_lt_i32 s13, 0x4000
	s_cselect_b32 s1, s1, 0
	s_cselect_b32 s0, s13, s0
	s_cselect_b32 s14, s53, s57
	s_cselect_b32 s15, s52, s56
	s_lshl_b64 s[0:1], s[0:1], 14
	s_add_u32 s0, s15, s0
	s_addc_u32 s1, s14, s1
	v_lshl_add_u64 v[70:71], s[0:1], 0, v[130:131]
	v_add_co_u32_e32 v38, vcc, s10, v70
	global_load_dwordx4 v[34:37], v130, s[0:1] nt
	global_load_dwordx4 v[30:33], v130, s[0:1] offset:1024 nt
	global_load_dwordx4 v[26:29], v130, s[0:1] offset:2048 nt
	global_load_dwordx4 v[22:25], v130, s[0:1] offset:3072 nt
	v_addc_co_u32_e32 v39, vcc, 0, v71, vcc
	v_add_co_u32_e32 v54, vcc, 0x2000, v70
	global_load_dwordx4 v[50:53], v[38:39], off nt
	global_load_dwordx4 v[46:49], v[38:39], off offset:1024 nt
	global_load_dwordx4 v[42:45], v[38:39], off offset:2048 nt
	s_nop 0
	global_load_dwordx4 v[38:41], v[38:39], off offset:3072 nt
	v_addc_co_u32_e32 v55, vcc, 0, v71, vcc
	v_add_co_u32_e32 v70, vcc, 0x3000, v70
	global_load_dwordx4 v[66:69], v[54:55], off nt
	global_load_dwordx4 v[62:65], v[54:55], off offset:1024 nt
	global_load_dwordx4 v[58:61], v[54:55], off offset:2048 nt
	s_nop 0
	global_load_dwordx4 v[54:57], v[54:55], off offset:3072 nt
	v_addc_co_u32_e32 v71, vcc, 0, v71, vcc
	global_load_dwordx4 v[82:85], v[70:71], off nt
	global_load_dwordx4 v[78:81], v[70:71], off offset:1024 nt
	global_load_dwordx4 v[74:77], v[70:71], off offset:2048 nt
	s_nop 0
	global_load_dwordx4 v[70:73], v[70:71], off offset:3072 nt
	s_branch .LBB0_291
